# P6->P7a grid barrier dropped on a 256-workgroup grid: each workgroup takes the 16 chunk items whose rows it produced in P6a (workgroup barrier only); original order and barrier kept for other grid siz
# speedup vs baseline: 1.0116x; 1.0116x over previous
; __device__ __forceinline__ int lane_now() { int l; asm volatile("v_mbcnt_lo_u32_b32 %0, -1, 0\n\tv_mbcnt_hi_u32_b32 %0, -1, %0" : "=v"(l)); return l; }
; __device__ __forceinline__ unsigned xb_ld(unsigned* p)              { return __hip_atomic_load(p, __ATOMIC_RELAXED, __HIP_MEMORY_SCOPE_AGENT); }
; __device__ __forceinline__ unsigned xb_add(unsigned* p, unsigned v) { return __hip_atomic_fetch_add(p, v, __ATOMIC_RELAXED, __HIP_MEMORY_SCOPE_AGENT); }
; #define XB_SPIN(cond, bar) do { unsigned _sp = 0; while (cond) { __builtin_amdgcn_s_sleep(1); \
;     if ((++_sp & 255u) == 0u) { if (xb_ld(&(bar)[XB_TMO])) break; if (_sp > XB_SPIN_CAP) { atomicAdd(&(bar)[XB_TMO], 1u); break; } } } } while (0)
; __device__ __forceinline__ void xcd_barrier(const XcdBarrier& b) {
;     asm volatile("s_waitcnt vmcnt(0)" ::: "memory");
;     __syncthreads();
;     if (b.w0 && lane_now() == 0) {
;         unsigned* bar = b.bar;
;         __builtin_amdgcn_s_waitcnt(0);
;         unsigned nloc = b.st[0], nx = b.st[1];
;         if (nloc == 0u) { xcd_barrier_complete(bar, b.x, nloc, nx); b.st[0] = nloc; b.st[1] = nx; }
;         const unsigned old = xb_add(&bar[XB_XSUB(b.x)], 1u);
;         const unsigned gen = old / nloc;
;         if (old + 1u == (gen + 1u) * nloc) {
;             __builtin_amdgcn_fence(__ATOMIC_RELEASE, "agent");
;             asm volatile("s_waitcnt vmcnt(0)" ::: "memory");
;             const unsigned og = xb_add(&bar[XB_TOP], 1u);
;             const unsigned tg = og / nx;
;             if (og + 1u == (tg + 1u) * nx) xb_add(&bar[XB_TOPGEN], 1u);
;             else XB_SPIN(xb_ld(&bar[XB_TOPGEN]) == tg, bar);
;             __builtin_amdgcn_fence(__ATOMIC_ACQUIRE, "agent");
;             xb_add(&bar[XB_XGEN(b.x)], 1u);
;             asm volatile("s_waitcnt vmcnt(0)" ::: "memory");
;         } else {
;             XB_SPIN(xb_ld(&bar[XB_XGEN(b.x)]) == gen, bar);
;             __builtin_amdgcn_fence(__ATOMIC_ACQUIRE, "agent");
;             asm volatile("s_waitcnt vmcnt(0)" ::: "memory");
;         }
;     }
;     __syncthreads();
; __global__ void __launch_bounds__(512, 2) mega_fwd(Params p) {
;     ...
;     xcd_barrier(xbar);
.LBB0_866:
	s_waitcnt vmcnt(0)
	v_readlane_b32 s0, v244, 15
	v_readlane_b32 s1, v244, 16
	s_and_b64 vcc, exec, s[0:1]
	s_waitcnt lgkmcnt(0)
	s_barrier
	s_cmp_eq_u32 s94, 0x100
	s_cbranch_scc1 .LBB0_920
	s_cbranch_vccnz .LBB0_920
	v_mbcnt_lo_u32_b32 v0, -1, 0
	v_mbcnt_hi_u32_b32 v0, -1, v0
	s_nop 0
	v_cmp_eq_u32_e32 vcc, 0, v0
	s_and_saveexec_b64 s[0:1], vcc
	s_cbranch_execz .LBB0_919
	s_add_i32 s4, 0, 0x23fc0
	v_mov_b32_e32 v0, s4
	s_waitcnt vmcnt(0) expcnt(0) lgkmcnt(0)
	ds_read_b32 v2, v0
	s_add_i32 s4, 0, 0x23fc4
	v_mov_b32_e32 v0, s4
	ds_read_b32 v0, v0
	s_waitcnt lgkmcnt(1)
	v_cmp_ne_u32_e32 vcc, 0, v2
	s_cbranch_vccnz .LBB0_883
	v_readlane_b32 s4, v244, 1
	s_mul_i32 s46, s95, s4
	s_add_u32 s4, s92, 0xc0200
	s_addc_u32 s5, s93, 0
	s_add_u32 s6, s92, 0xc0400
	s_addc_u32 s7, s93, 0
	s_add_u32 s8, s92, 0xc0500
	s_addc_u32 s9, s93, 0
	s_add_u32 s10, s92, 0xc0600
	s_addc_u32 s11, s93, 0
	s_add_u32 s12, s92, 0xc0700
	s_addc_u32 s13, s93, 0
	s_add_u32 s14, s92, 0xc0800
	s_addc_u32 s15, s93, 0
	s_add_u32 s16, s92, 0xc0900
	s_addc_u32 s17, s93, 0
	s_add_u32 s18, s92, 0xc0a00
	s_addc_u32 s19, s93, 0
	s_add_u32 s20, s92, 0xc0b00
	s_addc_u32 s21, s93, 0
	s_add_u32 s22, s92, 0xc0c00
	s_addc_u32 s23, s93, 0
	s_add_u32 s24, s92, 0xc0d00
	s_addc_u32 s25, s93, 0
	s_add_u32 s26, s92, 0xc0e00
	s_addc_u32 s27, s93, 0
	s_add_u32 s28, s92, 0xc0f00
	s_addc_u32 s29, s93, 0
	s_add_u32 s30, s92, 0xc1000
	s_addc_u32 s31, s93, 0
	s_add_u32 s34, s92, 0xc1100
	s_addc_u32 s35, s93, 0
	s_add_u32 s36, s92, 0xc1200
	s_addc_u32 s37, s93, 0
	s_add_u32 s38, s92, 0xc1300
	s_mul_i32 s46, s46, s94
	s_addc_u32 s39, s93, 0
	s_mov_b32 s47, 1
	v_mov_b32_e32 v16, 0
	s_branch .LBB0_871

; #define LAS __attribute__((address_space(3)))
; __device__ __forceinline__ h16* chunk_base(const Params& p, int item) { return (h16*)(p.ws + WS_SC) + ((size_t)(item >> 7) * SEQ + (size_t)(item & 127) * 64) * 384; }
; #define lane (lane_now())
; __device__ __forceinline__ void chunk_load(const Params& p, int item, int tid, h16 (&raw)[48]) {
;     const h16* base = chunk_base(p, item) + (size_t)(8 * (tid >> 6)) * 384 + (tid & 63);
; #pragma unroll
;     for (int i = 0; i < 8; ++i)
; #pragma unroll
;         for (int vq = 0; vq < 6; ++vq) raw[i * 6 + vq] = base[(size_t)i * 384 + vq * 64];
; }
; __device__ __forceinline__ void chunk_pre(const Params& p, LAS unsigned char* lds, int item, int next_item, int tid, int wave, int lane, h16 (&raw)[48]) {
;     h16* base = chunk_base(p, item);
;     LAS bf16_t* At = (LAS bf16_t*)lds; LAS bf16_t* Bt = At + 64 * MS; LAS bf16_t* Kt = Bt + 64 * MS; LAS bf16_t* Rt = Kt + 64 * MS;
;     LAS bf16_t* BhT = Rt + 64 * MS; LAS bf16_t* KhT = BhT + 64 * MS; LAS bf16_t* VT = KhT + 64 * MS;
;     LAS bf16_t* Mak = VT + 64 * MS; LAS bf16_t* Mrb = Mak + 64 * MS; LAS bf16_t* Mrk = Mrb + 64 * MS;
;     LAS bf16_t* AbT = Bt; LAS bf16_t* P1T = Kt;
;     LAS float* Mab = (LAS float*)(lds + 92160); LAS float* GT = (LAS float*)(lds + 141312);
;     LAS bf16_t* AtT = (LAS bf16_t*)(lds + 108544); LAS bf16_t* RH2T = (LAS bf16_t*)(lds + 117760);
;     LAS float* TD = (LAS float*)(lds + 126976); LAS float* Toff = (LAS float*)(lds + 131072); LAS float* Wf = (LAS float*)(lds + 137216);
;     LAS bf16_t* Tb = At;
;     const int fr = lane & 15, fq = lane >> 4;
;     {
;         const int g = tid >> 6, k = tid & 63;
; __global__ void __launch_bounds__(512, 2) mega_fwd(Params p) {
;     ...
;       h16 raw[48]; if ((int)blockIdx.x < 32 * 128) chunk_load(p, (int)blockIdx.x, tid7, raw);
;       for (int it = blockIdx.x; it < 32 * 128; it += G) chunk_pre(p, lds, it, (it + G < 32 * 128) ? it + G : -1, tid7, wave, lane7, raw); }
.LBB0_920:
	s_add_u32 s6, s92, 0x13b00000
	s_addc_u32 s7, s93, 0
	s_cmpk_lt_i32 s82, 0x1000
	s_movk_i32 s53, 0x1000
	s_waitcnt lgkmcnt(0)
	s_barrier
	v_mbcnt_lo_u32_b32 v1, -1, 0
	v_mbcnt_hi_u32_b32 v1, -1, v1
	s_cbranch_scc0 .LBB0_945
	v_readlane_b32 s45, v244, 0
	s_lshr_b32 s100, s45, 6
	s_lshl_b32 s100, s100, 10
	s_and_b32 s101, s45, 63
	s_lshl_b32 s101, s101, 1
	s_or_b32 s100, s100, s101
	s_cmp_eq_u32 s94, 0x100
	s_cselect_b32 s45, s100, s45
	s_ashr_i32 s0, s45, 7
	s_ashr_i32 s1, s0, 31
	s_lshl_b32 s4, s45, 6
	s_lshl_b64 s[0:1], s[0:1], 13
	s_and_b32 s4, s4, 0x1fc0
	s_or_b32 s4, s0, s4
	s_mulk_i32 s1, 0x300
	s_mul_hi_u32 s5, s4, 0x300
	s_add_i32 s5, s5, s1
	s_mulk_i32 s4, 0x300
	v_add_u32_e32 v0, s86, v1
	s_add_u32 s4, s6, s4
	s_addc_u32 s5, s7, s5
	v_ashrrev_i32_e32 v2, 3, v0
	s_movk_i32 s0, 0x300
	s_waitcnt vmcnt(3)
	v_and_b32_e32 v4, -8, v2
	v_mov_b64_e32 v[2:3], s[4:5]
	v_and_b32_e32 v5, 63, v1
	v_mad_i64_i32 v[2:3], s[4:5], v4, s0, v[2:3]
	v_lshlrev_b32_e32 v20, 1, v5
	v_mov_b32_e32 v21, 0
	v_lshl_add_u64 v[2:3], v[2:3], 0, v[20:21]
	global_load_ushort v40, v[2:3], off
	global_load_ushort v41, v[2:3], off offset:128
	global_load_ushort v42, v[2:3], off offset:256
	global_load_ushort v43, v[2:3], off offset:384
	global_load_ushort v44, v[2:3], off offset:512
	global_load_ushort v45, v[2:3], off offset:640
	global_load_ushort v46, v[2:3], off offset:768
	global_load_ushort v47, v[2:3], off offset:896
	global_load_ushort v48, v[2:3], off offset:1024
	global_load_ushort v49, v[2:3], off offset:1152
	global_load_ushort v50, v[2:3], off offset:1280
	global_load_ushort v51, v[2:3], off offset:1408
	global_load_ushort v52, v[2:3], off offset:1536
	global_load_ushort v53, v[2:3], off offset:1664
	global_load_ushort v54, v[2:3], off offset:1792
	global_load_ushort v55, v[2:3], off offset:1920
	global_load_ushort v56, v[2:3], off offset:2048
	global_load_ushort v57, v[2:3], off offset:2176
	global_load_ushort v58, v[2:3], off offset:2304
	global_load_ushort v59, v[2:3], off offset:2432
	global_load_ushort v60, v[2:3], off offset:2560
	global_load_ushort v61, v[2:3], off offset:2688
	global_load_ushort v62, v[2:3], off offset:2816
	global_load_ushort v64, v[2:3], off offset:2944
	global_load_ushort v66, v[2:3], off offset:3072
	global_load_ushort v67, v[2:3], off offset:3200
	global_load_ushort v68, v[2:3], off offset:3328
	global_load_ushort v69, v[2:3], off offset:3456
	global_load_ushort v70, v[2:3], off offset:3584
	global_load_ushort v71, v[2:3], off offset:3712
	global_load_ushort v72, v[2:3], off offset:3840
	global_load_ushort v73, v[2:3], off offset:3968
	v_add_co_u32_e32 v2, vcc, s53, v2
	v_and_b32_e32 v6, 15, v1
	s_nop 0
	v_addc_co_u32_e32 v3, vcc, 0, v3, vcc
	global_load_ushort v75, v[2:3], off
	global_load_ushort v76, v[2:3], off offset:128
	global_load_ushort v78, v[2:3], off offset:256
	global_load_ushort v80, v[2:3], off offset:384
	global_load_ushort v81, v[2:3], off offset:512
	global_load_ushort v82, v[2:3], off offset:640
	global_load_ushort v83, v[2:3], off offset:768
	global_load_ushort v84, v[2:3], off offset:896
	global_load_ushort v85, v[2:3], off offset:1024
	global_load_ushort v86, v[2:3], off offset:1152
	global_load_ushort v87, v[2:3], off offset:1280
	global_load_ushort v88, v[2:3], off offset:1408
	global_load_ushort v89, v[2:3], off offset:1536
	global_load_ushort v90, v[2:3], off offset:1664
	global_load_ushort v92, v[2:3], off offset:1792
	global_load_ushort v93, v[2:3], off offset:1920
	v_ashrrev_i32_e32 v2, 6, v0
	v_cmp_lt_i32_e64 s[4:5], 1, v2
	v_cmp_eq_u32_e64 s[46:47], 0, v6
	v_cmp_lt_i32_e64 s[82:83], 0, v2
	v_writelane_b32 v244, s4, 33
	v_cndmask_b32_e64 v101, 0, 1.0, s[46:47]
	v_cmp_eq_u32_e64 s[46:47], 1, v6
	v_writelane_b32 v244, s5, 34
	v_cmp_lt_i32_e64 s[4:5], 2, v2
	v_cndmask_b32_e64 v103, 0, 1.0, s[46:47]
	v_cmp_eq_u32_e64 s[46:47], 2, v6
	v_writelane_b32 v244, s4, 35
	s_add_i32 s8, 0, 0x1a800
	v_cndmask_b32_e64 v104, 0, 1.0, s[46:47]
	v_writelane_b32 v244, s5, 36
	v_cmp_lt_i32_e64 s[4:5], 3, v2
	v_cmp_eq_u32_e64 s[46:47], 3, v6
	v_ashrrev_i32_e32 v7, 4, v1
	v_writelane_b32 v244, s4, 37
	v_cndmask_b32_e64 v105, 0, 1.0, s[46:47]
	v_cmp_eq_u32_e64 s[46:47], 4, v6
	v_writelane_b32 v244, s5, 38
	v_cmp_lt_i32_e64 s[4:5], 4, v2
	v_cndmask_b32_e64 v106, 0, 1.0, s[46:47]
	v_cmp_eq_u32_e64 s[46:47], 5, v6
	v_writelane_b32 v244, s4, 39
	s_movk_i32 s79, 0x90
	v_cndmask_b32_e64 v107, 0, 1.0, s[46:47]
	v_writelane_b32 v244, s5, 40
	v_cmp_lt_i32_e64 s[4:5], 5, v2
	v_cmp_eq_u32_e64 s[46:47], 6, v6
	s_waitcnt vmcnt(50)
	v_mov_b32_e32 v10, 0x900
	v_writelane_b32 v244, s4, 41
	v_cndmask_b32_e64 v108, 0, 1.0, s[46:47]
	v_cmp_eq_u32_e64 s[46:47], 7, v6
	v_writelane_b32 v244, s5, 42
	v_cmp_lt_i32_e64 s[4:5], 6, v2
	v_cndmask_b32_e64 v109, 0, 1.0, s[46:47]
	v_cmp_eq_u32_e64 s[46:47], 8, v6
	v_writelane_b32 v244, s4, 43
	v_lshlrev_b32_e32 v100, 1, v6
	v_cndmask_b32_e64 v110, 0, 1.0, s[46:47]
	v_writelane_b32 v244, s5, 44
	v_cmp_lt_i32_e64 s[4:5], 7, v2
	v_cmp_eq_u32_e64 s[46:47], 9, v6
	s_add_i32 s1, 0, 0x22800
	v_writelane_b32 v244, s4, 45
	v_cndmask_b32_e64 v111, 0, 1.0, s[46:47]
	v_cmp_eq_u32_e64 s[46:47], 10, v6
	v_writelane_b32 v244, s5, 46
	s_movk_i32 s4, 0x240
	v_mul_lo_u32 v3, v2, s4
	v_or_b32_e32 v3, v3, v5
	v_lshl_add_u32 v74, v3, 1, 0
	v_mul_u32_u24_e32 v3, 0x48, v5
	v_lshlrev_b32_e32 v3, 1, v3
	v_lshlrev_b32_e32 v2, 4, v2
	v_add3_u32 v77, 0, v3, v2
	v_add3_u32 v79, s8, v3, v2
	v_mov_b64_e32 v[2:3], s[6:7]
	v_mad_i64_i32 v[2:3], s[4:5], v4, s0, v[2:3]
	v_readlane_b32 s4, v244, 14
	s_lshl_b32 s4, s4, 3
	s_and_b32 s4, s4, 0x1ffffff0
	v_or_b32_e32 v4, s4, v6
	v_readlane_b32 s4, v244, 20
	v_cndmask_b32_e64 v112, 0, 1.0, s[46:47]
	v_cmp_eq_u32_e64 s[46:47], 11, v6
	v_lshl_add_u64 v[22:23], v[2:3], 0, v[20:21]
	s_and_b32 s4, s4, 32
	v_and_b32_e32 v20, -16, v0
	v_cndmask_b32_e64 v113, 0, 1.0, s[46:47]
	v_cmp_eq_u32_e64 s[46:47], 12, v6
	v_mul_lo_u32 v2, v4, s79
	v_or_b32_e32 v3, s4, v6
	v_lshl_add_u32 v24, v7, 2, s4
	s_add_i32 s5, 0, 0x12000
	v_lshlrev_b32_e32 v25, 2, v20
	v_lshlrev_b32_e32 v26, 1, v20
	v_mul_lo_u32 v38, v20, s79
	v_lshlrev_b32_e32 v20, 8, v20
	v_cndmask_b32_e64 v114, 0, 1.0, s[46:47]
	v_cmp_eq_u32_e64 s[46:47], 13, v6
	v_mul_u32_u24_e32 v9, 0x90, v3
	v_mad_u32_u24 v10, v3, s79, v10
	v_lshlrev_b32_e32 v3, 8, v4
	s_add_i32 s18, 0, 0x16800
	s_waitcnt vmcnt(49)
; __device__ __forceinline__ void chunk_pre(const Params& p, LAS unsigned char* lds, int item, int next_item, int tid, int wave, int lane, h16 (&raw)[48]) {
;     ...
;     const int a0 = 16 * (wave >> 1), ar = a0 + fr;
;     {
;         f32x4 acc[2];
; #pragma unroll
;         for (int which = 0; which < 4; ++which) {
;             acc[0] = (f32x4){0.f, 0.f, 0.f, 0.f}; acc[1] = acc[0];
;             mm64((which & 1) ? Kt : Bt, (which & 2) ? Rt : At, acc, wave, fr, fq);
; #pragma unroll
;             for (int nt = 0; nt < 2; ++nt) { const int s0 = 32 * (wave & 1) + 16 * nt + 4 * fq; f32x4 v = acc[nt];
; #pragma unroll
;                 for (int jj = 0; jj < 4; ++jj) { const bool keep = (which & 2) ? (s0 + jj <= ar) : (s0 + jj < ar); if (!keep) v[jj] = 0.f; }
;                 if (which == 0) *(LAS f32x4*)(Mab + ar * 64 + s0) = v;
;                 else st_bf4(((which == 1) ? Mak : (which == 2) ? Mrb : Mrk) + ar * MS + s0, v); }
;         }
;     }
;     BAR_LDS();
;     {
;         f32x4 acc[2]; acc[0] = (f32x4){0.f, 0.f, 0.f, 0.f}; acc[1] = acc[0];
;         mm64(Mak, VT, acc, wave, fr, fq);
; #pragma unroll
;         for (int nt = 0; nt < 2; ++nt) st_bf4(RH2T + ar * MS + 32 * (wave & 1) + 16 * nt + 4 * fq, acc[nt]);
;     }
;     for (int e = tid; e < 6 * 256; e += 512) { const int ub = e >> 8, i = (e >> 4) & 15, j = e & 15;
;         const int r = ub < 3 ? 0 : ub < 5 ? 1 : 2, c = ub < 3 ? ub + 1 : ub < 5 ? ub - 1 : 3; Tb[(16 * r + i) * MS + 16 * c + j] = 0; }
;     if (tid < 64) {
;         const int r = tid >> 4, j = tid & 15; float x[16];
; #pragma unroll
;         for (int i = 0; i < 16; ++i) x[i] = 0.f;
; #pragma unroll
;         for (int i = 0; i < 16; ++i) {
;             const LAS float* mrow = Mab + (16 * r + i) * 64 + 16 * r;
;             float v = (i == j) ? 1.f : 0.f;
; #pragma unroll
;             for (int q = 0; q < (i + 3) / 4; ++q) { const f32x4 m4 = *(const LAS f32x4*)(mrow + 4 * q);
;                 v += (m4.x * x[4 * q] + m4.y * x[4 * q + 1]) + (m4.z * x[4 * q + 2] + m4.w * x[4 * q + 3]); }
;             x[i] = v; TD[r * 256 + i * 16 + j] = v; Tb[(16 * r + i) * MS + 16 * r + j] = (bf16_t)(pk2(v, 0.f) & 0xffffu);
;         }
;     }
;     BAR_LDS();
;     ...
;     for (int e = tid; e < 3 * 256; e += 512) { const int bk = e >> 8, i = (e >> 4) & 15, j = e & 15; Wf[bk * 256 + i * 16 + j] = M16(bk + 1, bk, TD + bk * 256); }
;     BAR_LDS();
	v_lshlrev_b32_e32 v15, 2, v24
	s_waitcnt vmcnt(48)
	v_add_u32_e32 v19, s5, v2
	s_add_i32 s5, 0, 0x14400
	v_add3_u32 v36, 0, v26, v100
	v_lshlrev_b32_e32 v26, 6, v0
	v_or_b32_e32 v39, 0x100, v20
	v_or_b32_e32 v144, 0x200, v20
	v_or_b32_e32 v145, 0x300, v20
	v_or_b32_e32 v146, 0x400, v20
	v_or_b32_e32 v147, 0x500, v20
	v_or_b32_e32 v148, 0x600, v20
	v_or_b32_e32 v149, 0x700, v20
	v_or_b32_e32 v150, 0x800, v20
	v_or_b32_e32 v151, 0x900, v20
	v_or_b32_e32 v152, 0xa00, v20
	v_or_b32_e32 v153, 0xb00, v20
	v_or_b32_e32 v154, 0xc00, v20
	v_or_b32_e32 v155, 0xd00, v20
	v_cndmask_b32_e64 v115, 0, 1.0, s[46:47]
	v_or_b32_e32 v156, 0xe00, v20
	v_cmp_eq_u32_e64 s[46:47], 14, v6
	v_or_b32_e32 v20, 15, v0
	v_lshl_add_u32 v65, v5, 2, s1
	v_lshlrev_b32_e32 v5, 3, v7
	v_add_u32_e32 v7, 0, v2
	v_add3_u32 v94, s18, v3, v15
	v_lshlrev_b32_e32 v3, 1, v24
	v_add_u32_e32 v28, s5, v2
	s_add_i32 s5, 0, 0x1cc00
	v_lshlrev_b32_e32 v98, 2, v6
	v_and_b32_e32 v37, 0xfffffc00, v26
	v_cndmask_b32_e64 v116, 0, 1.0, s[46:47]
	v_lshlrev_b32_e32 v157, 8, v20
	v_cmp_eq_u32_e64 s[46:47], 15, v6
	v_mul_lo_u32 v6, v20, s79
	v_ashrrev_i32_e32 v20, 8, v0
	v_ashrrev_i32_e32 v26, 4, v0
	v_add_u32_e32 v95, v7, v3
	v_add_u32_e32 v96, v19, v3
	v_add_u32_e32 v97, v28, v3
	v_add_u32_e32 v3, s5, v2
	s_movk_i32 s5, 0x600
	v_and_b32_e32 v27, 15, v26
	v_add_u32_e32 v29, 2, v20
	v_cmp_gt_i32_e64 s[10:11], s5, v0
	v_lshl_or_b32 v30, v29, 4, v27
	v_lshl_add_u32 v31, v30, 8, s18
	v_writelane_b32 v244, s10, 47
	v_lshlrev_b32_e32 v32, 6, v20
	v_cvt_pk_bf16_f32 v102, v101, s0
	v_writelane_b32 v244, s11, 48
	v_cmp_gt_i32_e64 s[10:11], 64, v0
	v_cndmask_b32_e64 v117, 0, 1.0, s[46:47]
	v_cmp_gt_i32_e64 s[46:47], s0, v0
	s_add_i32 s42, 0, 0x21800
	v_add_u32_e32 v119, v31, v32
	v_and_b32_e32 v31, 0x3fffff00, v0
	s_add_i32 s43, 0, 0x20000
	s_add_i32 s0, 0, 0x20c00
	v_lshlrev_b32_e32 v8, 2, v0
	v_writelane_b32 v244, s10, 49
	v_add_u32_e32 v118, s42, v98
	v_lshlrev_b32_e32 v31, 2, v31
	v_add_u32_e32 v121, s43, v98
	v_add_u32_e32 v128, s0, v98
	s_add_i32 s0, 0, 0x1fc00
	v_add_u32_e32 v63, s1, v8
	v_writelane_b32 v244, s11, 50
	s_add_i32 s19, 0, 0x1f000
	v_add_u32_e32 v122, v121, v31
	v_lshlrev_b32_e32 v27, 6, v27
	v_add_u32_e32 v123, v118, v31
	v_lshlrev_b32_e32 v29, 10, v29
	v_add_u32_e32 v130, s0, v25
	v_lshl_add_u32 v136, v4, 2, s1
	v_cmp_eq_u32_e64 s[0:1], v24, v4
	v_and_b32_e32 v1, -16, v1
	v_or_b32_e32 v12, 1, v24
	v_add_u32_e32 v124, v123, v27
	v_add3_u32 v125, s19, v29, v27
	v_add_u32_e32 v126, v122, v27
	v_mul_lo_u32 v27, v30, s79
	v_writelane_b32 v244, s0, 51
	v_add_u32_e32 v91, v7, v1
	v_add_u32_e32 v11, 0, v1
	v_add_u32_e32 v27, 0, v27
	v_lshlrev_b32_e32 v20, 5, v20
	v_add3_u32 v132, s8, v2, v1
	v_add_u32_e32 v133, v3, v1
	v_add_u32_e32 v134, v19, v1
	v_mul_lo_u32 v2, v4, 6
	v_add_u32_e32 v135, v28, v1
	v_writelane_b32 v244, s1, 52
	v_cmp_eq_u32_e64 s[0:1], v12, v4
	v_max_i32_e32 v1, 0x400, v0
	v_or_b32_e32 v13, 2, v24
	s_lshl_b32 s4, s4, 1
	v_add3_u32 v127, v27, v20, v100
	v_add_u32_e32 v20, 2, v2
	v_writelane_b32 v244, s0, 53
	v_sub_u32_e32 v1, v1, v0
	v_add_u32_e32 v34, s4, v3
	v_add_u32_e32 v99, s19, v98
	v_lshlrev_b32_e32 v162, 8, v26
	v_add_u32_e32 v129, s42, v8
	v_mul_lo_u32 v8, v26, s79
	v_lshlrev_b64 v[26:27], 7, v[20:21]
	v_add_u32_e32 v20, 3, v2
	v_mov_b32_e32 v3, v21
	v_writelane_b32 v244, s1, 54
	v_cmp_eq_u32_e64 s[0:1], v13, v4
	v_add_u32_e32 v1, 0x1ff, v1
	v_or_b32_e32 v14, 3, v24
	v_add_u32_e32 v15, 16, v24
	v_add_u32_e32 v16, 17, v24
	v_add_u32_e32 v17, 18, v24
	v_add_u32_e32 v18, 19, v24
	s_movk_i32 s5, 0x100
	v_add_u32_e32 v120, v99, v31
	v_lshlrev_b64 v[28:29], 7, v[20:21]
	v_lshlrev_b64 v[30:31], 7, v[2:3]
	v_writelane_b32 v244, s0, 55
	v_or_b32_e32 v20, 1, v2
	v_lshrrev_b32_e32 v2, 9, v1
	s_movk_i32 s8, 0x5ff
	v_cmp_lt_i32_e64 s[20:21], v24, v4
	v_cmp_lt_i32_e32 vcc, v12, v4
	v_cmp_lt_i32_e64 s[70:71], v13, v4
	v_cmp_lt_i32_e64 s[22:23], v14, v4
	v_cmp_lt_i32_e64 s[24:25], v15, v4
	v_cmp_lt_i32_e64 s[76:77], v16, v4
	v_cmp_lt_i32_e64 s[74:75], v17, v4
	v_cmp_lt_i32_e64 s[26:27], v18, v4
	v_cmp_gt_i32_e64 s[28:29], v24, v4
	v_cmp_gt_i32_e64 s[30:31], v13, v4
	v_cmp_gt_i32_e64 s[34:35], v14, v4
	v_cmp_gt_i32_e64 s[36:37], v15, v4
	v_cmp_gt_i32_e64 s[38:39], v17, v4
	v_cmp_gt_i32_e64 s[40:41], v18, v4
	v_cmp_gt_i32_e64 s[48:49], s5, v0
	v_add_u32_e32 v7, s4, v7
	v_writelane_b32 v244, s1, 56
	v_cmp_eq_u32_e64 s[56:57], v14, v4
	v_cmp_eq_u32_e64 s[88:89], v15, v4
	v_cmp_eq_u32_e64 s[4:5], v16, v4
	v_cmp_eq_u32_e64 s[0:1], v17, v4
	v_cmp_eq_u32_e64 s[68:69], v18, v4
	v_add_u32_e32 v4, 1, v2
	v_cmp_lt_u32_e64 s[10:11], s8, v1
	v_and_b32_e32 v137, 0xfffffc, v4
	v_add_u32_e32 v35, s18, v25
	v_writelane_b32 v244, s10, 57
	s_or_b64 s[70:71], s[22:23], s[70:71]
	s_or_b64 s[74:75], s[26:27], s[74:75]
	v_writelane_b32 v244, s11, 58
	v_cmp_ne_u32_e64 s[10:11], v4, v137
	s_mov_b32 s9, 0
	v_add3_u32 v131, 0, v8, v100
	v_ashrrev_i32_e32 v25, 31, v24
	v_lshlrev_b64 v[32:33], 7, v[20:21]
	v_lshl_add_u32 v138, v137, 9, v0
	v_add_u32_e32 v3, 0x600, v0
	v_add_u32_e32 v2, 0x400, v0
	v_add_u32_e32 v1, 0x200, v0
	v_writelane_b32 v244, s10, 59
	v_add_u32_e32 v139, v11, v10
	v_add_u32_e32 v140, v34, v5
	v_add_u32_e32 v141, v99, v37
	v_add_u32_e32 v142, v36, v38
	v_add_u32_e32 v143, v35, v39
	v_add_u32_e32 v144, v35, v144
	v_add_u32_e32 v145, v35, v145
	v_add_u32_e32 v146, v35, v146
	v_add_u32_e32 v147, v35, v147
	v_add_u32_e32 v148, v35, v148
	v_add_u32_e32 v149, v35, v149
	v_add_u32_e32 v150, v35, v150
	v_add_u32_e32 v151, v35, v151
	v_add_u32_e32 v152, v35, v152
	v_add_u32_e32 v153, v35, v153
	v_add_u32_e32 v154, v35, v154
	v_add_u32_e32 v155, v35, v155
	v_add_u32_e32 v156, v35, v156
	v_add_u32_e32 v157, v35, v157
	v_add_u32_e32 v158, v36, v6
	s_movk_i32 s44, 0xff
	v_add_u32_e32 v159, v7, v5
	v_mov_b32_e32 v160, 0x300
	v_add_u32_e32 v161, v11, v9
	s_or_b64 s[72:73], s[70:71], vcc
	s_or_b64 s[76:77], s[74:75], s[76:77]
	v_add_u32_e32 v162, s18, v162
	v_writelane_b32 v244, s11, 60
	s_mov_b64 s[100:101], vcc
	v_cmp_gt_u32_e32 vcc, 0xc0, v0
	s_mov_b64 s[98:99], vcc
	v_lshrrev_b32_e32 v213, 1, v0
	v_and_b32_e32 v212, 1, v0
	v_lshrrev_b32_e32 v216, 4, v213
	v_and_b32_e32 v213, 15, v213
	v_cmp_lt_u32_e32 vcc, 2, v216
	s_nop 1
	v_cndmask_b32_e64 v217, 0, 1, vcc
	v_cmp_lt_u32_e32 vcc, 4, v216
	s_nop 1
	v_cndmask_b32_e64 v218, 0, 1, vcc
	v_add_u32_e32 v219, v217, v218
	v_lshl_add_u32 v213, v219, 4, v213
	v_add_u32_e32 v216, 1, v216
	v_lshlrev_b32_e32 v217, 1, v217
	v_sub_u32_e32 v216, v216, v217
	v_sub_u32_e32 v216, v216, v218
	v_lshlrev_b32_e32 v216, 5, v216
	v_lshl_add_u32 v212, v212, 4, v216
	v_mov_b32_e32 v217, 0x90
	v_mad_u32_u24 v212, v213, v217, v212
	v_mov_b32_e32 v214, 0
	v_mov_b32_e32 v215, 0
	s_mov_b64 vcc, s[100:101]
	s_branch .LBB0_923

; #define BAR_LDS() do { asm volatile("s_waitcnt lgkmcnt(0)" ::: "memory"); __builtin_amdgcn_s_barrier(); asm volatile("" ::: "memory"); } while (0)
; __device__ __forceinline__ unsigned pk2(float lo, float hi) { const f32x2c v = {lo, hi}; const bf16x2c b = __builtin_convertvector(v, bf16x2c); return __builtin_bit_cast(unsigned, b); }
; __device__ __forceinline__ void chunk_pre(const Params& p, LAS unsigned char* lds, int item, int next_item, int tid, int wave, int lane, h16 (&raw)[48]) {
;     ...
;         const int g = tid >> 6, k = tid & 63;
;         float wv[8], lp[8];
; #pragma unroll
;         for (int i = 0; i < 8; ++i) wv[i] = (float)raw[i * 6 + 2];
;         lp[0] = wv[0];
; #pragma unroll
;         for (int i = 1; i < 8; ++i) lp[i] = lp[i - 1] * wv[i];
;         GT[g * 64 + k] = lp[7];
;         BAR_LDS();
;         float bs = 1.f, WL = 1.f;
; #pragma unroll
;         for (int q = 0; q < 8; ++q) { const float gq = GT[q * 64 + k]; if (q < g) bs *= gq; WL *= gq; }
;         float bhv[8], khv[8], vtv[8], atv[8];
; #pragma unroll
;         for (int i = 0; i < 8; ++i) {
;             const int t = 8 * g + i;
;             const float kk = (float)raw[i * 6 + 0], wr = (float)raw[i * 6 + 1], bb = (float)raw[i * 6 + 3], kx = (float)raw[i * 6 + 4], vv = (float)raw[i * 6 + 5];
;             const float Wt = bs * lp[i], Wp = (i == 0) ? bs : bs * lp[i - 1], iW = 1.f / Wt;
;             atv[i] = -kk * Wp; At[t * MS + k] = (bf16_t)(pk2(-kk * Wp, 0.f) & 0xffffu); Rt[t * MS + k] = (bf16_t)(pk2(wr * Wp, 0.f) & 0xffffu);
;             Bt[t * MS + k] = (bf16_t)(pk2(bb * iW, 0.f) & 0xffffu); Kt[t * MS + k] = (bf16_t)(pk2(kx * iW, 0.f) & 0xffffu);
;             bhv[i] = bb * iW * WL; khv[i] = kx * iW * WL; vtv[i] = vv;
;         }
.LBB0_923:
	s_waitcnt vmcnt(45)
	v_cvt_f32_f16_e32 v10, v42
	s_waitcnt vmcnt(39)
	v_cvt_f32_f16_e32 v4, v48
	s_waitcnt vmcnt(33)
	v_cvt_f32_f16_e32 v5, v54
	s_waitcnt vmcnt(27)
	v_cvt_f32_f16_e32 v6, v60
	s_waitcnt vmcnt(21)
	v_cvt_f32_f16_e32 v12, v68
	s_waitcnt vmcnt(15)
	v_cvt_f32_f16_e32 v13, v75
	v_mul_f32_e32 v11, v10, v4
	s_waitcnt vmcnt(9)
	v_cvt_f32_f16_e32 v14, v83
	v_mul_f32_e32 v34, v11, v5
	s_waitcnt vmcnt(3)
	v_cvt_f32_f16_e32 v15, v89
	v_mul_f32_e32 v35, v34, v6
	v_mul_f32_e32 v12, v35, v12
	v_mul_f32_e32 v13, v12, v13
	v_mul_f32_e32 v4, v13, v14
	v_mul_f32_e32 v5, v4, v15
	ds_write_b32 v63, v5
	s_waitcnt lgkmcnt(0)
	s_barrier
	ds_read2st64_b32 v[14:15], v65 offset1:1
	ds_read2st64_b32 v[220:221], v65 offset0:2 offset1:3
	ds_read2st64_b32 v[222:223], v65 offset0:4 offset1:5
	ds_read2st64_b32 v[224:225], v65 offset0:6 offset1:7
	v_readlane_b32 s14, v244, 33
	v_readlane_b32 s15, v244, 34
	v_cvt_f32_f16_e64 v37, -v40
	v_cvt_f32_f16_e32 v36, v41
	s_waitcnt lgkmcnt(3)
	v_cndmask_b32_e64 v6, 1.0, v14, s[82:83]
	v_mul_f32_e32 v16, v6, v15
	v_cndmask_b32_e64 v6, v6, v16, s[14:15]
	v_mul_f32_e32 v16, v14, v15
	s_nop 0
	v_readlane_b32 s14, v244, 35
	v_readlane_b32 s15, v244, 36
	v_cvt_f32_f16_e32 v17, v51
	v_cvt_f32_f16_e64 v170, -v46
	s_waitcnt lgkmcnt(2)
	v_mul_f32_e32 v168, v220, v6
	v_cndmask_b32_e64 v6, v6, v168, s[14:15]
	v_readlane_b32 s14, v244, 37
	v_mul_f32_e32 v14, v16, v220
	v_mul_f32_e32 v16, v221, v6
	v_readlane_b32 s15, v244, 38
	v_cvt_f32_f16_e32 v171, v47
	v_cvt_f32_f16_e32 v174, v53
	v_cndmask_b32_e64 v6, v6, v16, s[14:15]
	v_mul_f32_e32 v16, v14, v221
	s_nop 0
	v_readlane_b32 s14, v244, 39
	v_readlane_b32 s15, v244, 40
	v_cvt_f32_f16_e32 v18, v55
	v_cvt_f32_f16_e32 v19, v61
	s_waitcnt lgkmcnt(1)
	v_mul_f32_e32 v168, v222, v6
	v_cndmask_b32_e64 v6, v6, v168, s[14:15]
	v_readlane_b32 s14, v244, 41
	v_mul_f32_e32 v14, v16, v222
	v_mul_f32_e32 v16, v223, v6
	v_readlane_b32 s15, v244, 42
	v_cvt_f32_f16_e32 v176, v59
	v_cvt_f32_f16_e32 v177, v67
	v_cndmask_b32_e64 v6, v6, v16, s[14:15]
	v_mul_f32_e32 v16, v14, v223
	s_nop 0
	v_readlane_b32 s14, v244, 43
	v_readlane_b32 s15, v244, 44
	v_cvt_f32_f16_e32 v169, v73
	v_cvt_f32_f16_e32 v8, v69
	s_waitcnt lgkmcnt(0)
	v_mul_f32_e32 v168, v224, v6
	v_cndmask_b32_e64 v6, v6, v168, s[14:15]
	v_readlane_b32 s14, v244, 45
	v_mul_f32_e32 v14, v16, v224
	v_mul_f32_e32 v16, v225, v6
	v_readlane_b32 s15, v244, 46
	v_cvt_f32_f16_e32 v9, v76
	v_cvt_f32_f16_e32 v7, v45
	v_cndmask_b32_e64 v16, v6, v16, s[14:15]
	v_mul_f32_e32 v168, v16, v37
	v_mul_f32_e32 v6, v14, v225
	v_cvt_pk_bf16_f32 v14, v168, s0
	ds_write_b16 v74, v14
	v_mul_f32_e32 v14, v16, v36
	v_pk_mul_f32 v[36:37], v[16:17], v[10:11] op_sel_hi:[0,1]
	v_div_scale_f32 v10, s[14:15], v37, v37, 1.0
	v_rcp_f32_e32 v11, v10
	v_cvt_pk_bf16_f32 v14, v14, s0
	ds_write_b16 v74, v14 offset:27648
	v_cvt_f32_f16_e32 v14, v43
	v_fma_f32 v172, -v10, v11, 1.0
	v_fmac_f32_e32 v11, v172, v11
	v_div_scale_f32 v172, vcc, 1.0, v37, 1.0
	v_mul_f32_e32 v173, v172, v11
	v_fma_f32 v175, -v10, v173, v172
	v_fmac_f32_e32 v173, v175, v11
	v_fma_f32 v10, -v10, v173, v172
	v_div_fmas_f32 v10, v10, v11, v173
	v_div_fixup_f32 v173, v10, v37, 1.0
	v_div_scale_f32 v10, s[14:15], v36, v36, 1.0
	v_rcp_f32_e32 v11, v10
	v_cvt_f32_f16_e32 v15, v49
	v_mul_f32_e32 v170, v36, v170
	v_pk_mul_f32 v[12:13], v[12:13], v[16:17] op_sel_hi:[1,0]
	v_fma_f32 v172, -v10, v11, 1.0
	v_fmac_f32_e32 v11, v172, v11
	v_div_scale_f32 v172, vcc, 1.0, v36, 1.0
	v_mul_f32_e32 v175, v172, v11
	v_fma_f32 v178, -v10, v175, v172
	v_fmac_f32_e32 v175, v178, v11
	v_fma_f32 v10, -v10, v175, v172
	v_div_fmas_f32 v10, v10, v11, v175
	v_div_fixup_f32 v172, v10, v36, 1.0
	v_pk_mul_f32 v[10:11], v[172:173], v[14:15]
	v_cvt_f32_f16_e32 v15, v50
	v_cvt_pk_bf16_f32 v14, v10, s0
	ds_write_b16 v74, v14 offset:9216
	v_cvt_pk_bf16_f32 v14, v170, s0
	ds_write_b16 v74, v14 offset:144
	v_mul_f32_e32 v14, v36, v171
	v_cvt_pk_bf16_f32 v14, v14, s0
	ds_write_b16 v74, v14 offset:27792
	v_cvt_pk_bf16_f32 v14, v11, s0
	ds_write_b16 v74, v14 offset:9360
	v_cvt_f32_f16_e32 v14, v44
	v_mul_f32_e32 v169, v12, v169
	v_cvt_pk_bf16_f32 v169, v169, s0
	ds_write_b16 v74, v169 offset:28368
	v_pk_mul_f32 v[14:15], v[172:173], v[14:15]
	v_pk_mul_f32 v[172:173], v[34:35], v[16:17] op_sel_hi:[1,0]
	v_cvt_pk_bf16_f32 v171, v14, s0
	v_div_scale_f32 v34, s[14:15], v173, v173, 1.0
	v_rcp_f32_e32 v35, v34
	ds_write_b16 v74, v171 offset:18432
	v_cvt_pk_bf16_f32 v171, v15, s0
	ds_write_b16 v74, v171 offset:18576
	v_mul_f32_e32 v171, v37, v174
	v_cvt_pk_bf16_f32 v171, v171, s0
	ds_write_b16 v74, v171 offset:27936
	v_fma_f32 v171, -v34, v35, 1.0
	v_fmac_f32_e32 v35, v171, v35
	v_div_scale_f32 v171, vcc, 1.0, v173, 1.0
	v_mul_f32_e32 v174, v171, v35
	v_fma_f32 v175, -v34, v174, v171
	v_fmac_f32_e32 v174, v175, v35
	v_fma_f32 v34, -v34, v174, v171
	v_div_fmas_f32 v34, v34, v35, v174
	v_div_fixup_f32 v175, v34, v173, 1.0
	v_div_scale_f32 v34, s[14:15], v172, v172, 1.0
	v_rcp_f32_e32 v35, v34
	v_pk_mov_b32 v[36:37], v[36:37], v[172:173] op_sel:[1,0]
	v_cvt_f32_f16_e32 v167, v82
	v_pk_mul_f32 v[4:5], v[4:5], v[16:17] op_sel_hi:[1,0]
	v_fma_f32 v171, -v34, v35, 1.0
	v_fmac_f32_e32 v35, v171, v35
	v_div_scale_f32 v171, vcc, 1.0, v172, 1.0
	v_mul_f32_e32 v174, v171, v35
	v_fma_f32 v178, -v34, v174, v171
	v_fmac_f32_e32 v174, v178, v35
	v_fma_f32 v34, -v34, v174, v171
	v_div_fmas_f32 v34, v34, v35, v174
	v_div_fixup_f32 v174, v34, v172, 1.0
	v_pk_mul_f32 v[34:35], v[174:175], v[18:19]
	v_cvt_f32_f16_e64 v19, -v58
	v_cvt_pk_bf16_f32 v18, v34, s0
	ds_write_b16 v74, v18 offset:9504
	v_cvt_f32_f16_e64 v18, -v52
	v_div_scale_f32 v16, s[14:15], v5, v5, 1.0
; #define LAS __attribute__((address_space(3)))
; __device__ __forceinline__ unsigned pk2(float lo, float hi) { const f32x2c v = {lo, hi}; const bf16x2c b = __builtin_convertvector(v, bf16x2c); return __builtin_bit_cast(unsigned, b); }
; __device__ __forceinline__ void chunk_pre(const Params& p, LAS unsigned char* lds, int item, int next_item, int tid, int wave, int lane, h16 (&raw)[48]) {
;     ...
;         for (int i = 0; i < 8; ++i) {
;             const int t = 8 * g + i;
;             const float kk = (float)raw[i * 6 + 0], wr = (float)raw[i * 6 + 1], bb = (float)raw[i * 6 + 3], kx = (float)raw[i * 6 + 4], vv = (float)raw[i * 6 + 5];
;             const float Wt = bs * lp[i], Wp = (i == 0) ? bs : bs * lp[i - 1], iW = 1.f / Wt;
;             atv[i] = -kk * Wp; At[t * MS + k] = (bf16_t)(pk2(-kk * Wp, 0.f) & 0xffffu); Rt[t * MS + k] = (bf16_t)(pk2(wr * Wp, 0.f) & 0xffffu);
;             Bt[t * MS + k] = (bf16_t)(pk2(bb * iW, 0.f) & 0xffffu); Kt[t * MS + k] = (bf16_t)(pk2(kx * iW, 0.f) & 0xffffu);
;             bhv[i] = bb * iW * WL; khv[i] = kx * iW * WL; vtv[i] = vv;
;         }
;         *(LAS u32x4*)(BhT + k * MS + 8 * g) = (u32x4){pk2(bhv[0], bhv[1]), pk2(bhv[2], bhv[3]), pk2(bhv[4], bhv[5]), pk2(bhv[6], bhv[7])};
;         *(LAS u32x4*)(KhT + k * MS + 8 * g) = (u32x4){pk2(khv[0], khv[1]), pk2(khv[2], khv[3]), pk2(khv[4], khv[5]), pk2(khv[6], khv[7])};
;         *(LAS u32x4*)(VT + k * MS + 8 * g) = (u32x4){pk2(vtv[0], vtv[1]), pk2(vtv[2], vtv[3]), pk2(vtv[4], vtv[5]), pk2(vtv[6], vtv[7])};
;         *(LAS u32x4*)(AtT + k * MS + 8 * g) = (u32x4){pk2(atv[0], atv[1]), pk2(atv[2], atv[3]), pk2(atv[4], atv[5]), pk2(atv[6], atv[7])};
;     }
;     if (next_item >= 0) chunk_load(p, next_item, tid, raw);
; __global__ void __launch_bounds__(512, 2) mega_fwd(Params p) {
;     ...
;       for (int it = blockIdx.x; it < 32 * 128; it += G) chunk_pre(p, lds, it, (it + G < 32 * 128) ? it + G : -1, tid7, wave, lane7, raw); }
	v_cvt_f32_f16_e32 v166, v88
	v_pk_mul_f32 v[18:19], v[36:37], v[18:19]
	v_cvt_f32_f16_e32 v37, v62
	v_cvt_pk_bf16_f32 v36, v18, s0
	ds_write_b16 v74, v36 offset:288
	v_cvt_pk_bf16_f32 v36, v19, s0
	ds_write_b16 v74, v36 offset:432
	v_mul_f32_e32 v36, v172, v176
	v_cvt_pk_bf16_f32 v36, v36, s0
	ds_write_b16 v74, v36 offset:28080
	v_cvt_pk_bf16_f32 v36, v35, s0
	ds_write_b16 v74, v36 offset:9648
	v_cvt_f32_f16_e32 v36, v56
	v_cvt_f32_f16_e64 v180, -v81
	v_cvt_f32_f16_e64 v181, -v87
	v_cvt_f32_f16_e32 v20, v57
	v_pk_mul_f32 v[36:37], v[174:175], v[36:37]
	v_cvt_f32_f16_e32 v38, v64
	v_cvt_pk_bf16_f32 v171, v36, s0
	ds_write_b16 v74, v171 offset:18720
	v_cvt_pk_bf16_f32 v171, v37, s0
	ds_write_b16 v74, v171 offset:18864
	v_mul_f32_e32 v171, v173, v177
	v_cvt_pk_bf16_f32 v171, v171, s0
	ds_write_b16 v74, v171 offset:28224
	v_div_scale_f32 v171, s[14:15], v13, v13, 1.0
	v_rcp_f32_e32 v174, v171
	v_pk_mov_b32 v[172:173], v[172:173], v[12:13] op_sel:[1,0]
	v_cvt_f32_f16_e32 v39, v71
	v_cvt_f32_f16_e32 v163, v80
	v_fma_f32 v175, -v171, v174, 1.0
	v_fmac_f32_e32 v174, v175, v174
	v_div_scale_f32 v175, vcc, 1.0, v13, 1.0
	v_mul_f32_e32 v176, v175, v174
	v_fma_f32 v177, -v171, v176, v175
	v_fmac_f32_e32 v176, v177, v174
	v_fma_f32 v171, -v171, v176, v175
	v_div_fmas_f32 v171, v171, v174, v176
	v_div_fixup_f32 v175, v171, v13, 1.0
	v_div_scale_f32 v171, s[14:15], v12, v12, 1.0
	v_rcp_f32_e32 v174, v171
	v_cvt_f32_f16_e32 v164, v86
	s_waitcnt vmcnt(0)
	v_cvt_f32_f16_e32 v165, v93
	s_add_i32 s50, s45, s94
	s_add_i32 s100, s45, 0x80
	s_and_b32 s101, s45, 0x380
	s_cmp_eq_u32 s101, 0x380
	s_cselect_b32 s101, 0xfffffc01, 0
	s_add_i32 s100, s100, s101
	s_and_b32 s101, s45, 0x381
	s_cmp_eq_u32 s101, 0x381
	s_cselect_b32 s100, 0x1000, s100
	s_cmp_eq_u32 s94, 0x100
	s_cselect_b32 s50, s100, s50
	v_fma_f32 v176, -v171, v174, 1.0
	v_fmac_f32_e32 v174, v176, v174
	v_div_scale_f32 v176, vcc, 1.0, v12, 1.0
	v_mul_f32_e32 v177, v176, v174
	v_fma_f32 v178, -v171, v177, v176
	v_fmac_f32_e32 v177, v178, v174
	v_fma_f32 v171, -v171, v177, v176
	v_div_fmas_f32 v171, v171, v174, v177
	v_cvt_f32_f16_e64 v176, -v66
	v_cvt_f32_f16_e64 v177, -v72
	v_div_fixup_f32 v174, v171, v12, 1.0
	v_pk_mul_f32 v[8:9], v[174:175], v[8:9]
	s_cmpk_gt_i32 s50, 0xfff
	v_cvt_pk_bf16_f32 v171, v8, s0
	v_pk_mul_f32 v[172:173], v[172:173], v[176:177]
	v_cvt_pk_bf16_f32 v169, v9, s0
	v_pk_mul_f32 v[176:177], v[6:7], v[8:9] op_sel_hi:[0,1]
	v_cvt_f32_f16_e32 v8, v70
	v_cvt_f32_f16_e32 v9, v78
	ds_write_b16 v74, v169 offset:9936
	ds_write_b16 v74, v171 offset:9792
	v_cvt_pk_bf16_f32 v171, v172, s0
	v_pk_mul_f32 v[8:9], v[174:175], v[8:9]
	ds_write_b16 v74, v171 offset:576
	v_cvt_pk_bf16_f32 v169, v8, s0
	v_pk_mul_f32 v[174:175], v[6:7], v[8:9] op_sel_hi:[0,1]
	v_mul_f32_e32 v8, v13, v167
	v_rcp_f32_e32 v167, v16
	ds_write_b16 v74, v169 offset:19008
	v_cvt_pk_bf16_f32 v169, v9, s0
	ds_write_b16 v74, v169 offset:19152
	v_fma_f32 v169, -v16, v167, 1.0
	v_cvt_pk_bf16_f32 v171, v173, s0
	v_fmac_f32_e32 v167, v169, v167
	v_div_scale_f32 v169, vcc, 1.0, v5, 1.0
	ds_write_b16 v74, v171 offset:720
	v_mul_f32_e32 v171, v169, v167
	v_fma_f32 v178, -v16, v171, v169
	v_fmac_f32_e32 v171, v178, v167
	v_fma_f32 v16, -v16, v171, v169
	v_div_fmas_f32 v16, v16, v167, v171
	v_div_fixup_f32 v179, v16, v5, 1.0
	v_div_scale_f32 v16, s[14:15], v4, v4, 1.0
	v_rcp_f32_e32 v167, v16
	v_cvt_pk_bf16_f32 v8, v8, s0
	ds_write_b16 v74, v8 offset:28512
	v_cvt_f32_f16_e32 v8, v84
	v_fma_f32 v169, -v16, v167, 1.0
	v_fmac_f32_e32 v167, v169, v167
	v_div_scale_f32 v169, vcc, 1.0, v4, 1.0
	v_mul_f32_e32 v171, v169, v167
	v_fma_f32 v178, -v16, v171, v169
	v_cvt_f32_f16_e32 v9, v90
	v_fmac_f32_e32 v171, v178, v167
	v_fma_f32 v16, -v16, v171, v169
	v_div_fmas_f32 v16, v16, v167, v171
	v_pk_mov_b32 v[12:13], v[12:13], v[4:5] op_sel:[1,0]
	v_div_fixup_f32 v178, v16, v4, 1.0
	v_pk_mul_f32 v[12:13], v[12:13], v[180:181]
	v_mul_f32_e32 v4, v4, v166
	v_pk_mul_f32 v[8:9], v[178:179], v[8:9]
	v_cvt_pk_bf16_f32 v5, v12, s0
	v_cvt_pk_bf16_f32 v4, v4, s0
	ds_write_b16 v74, v5 offset:864
	v_cvt_pk_bf16_f32 v5, v13, s0
	ds_write_b16 v74, v4 offset:28656
	v_cvt_pk_bf16_f32 v4, v9, s0
	v_cvt_pk_bf16_f32 v16, v8, s0
	ds_write_b16 v74, v5 offset:1008
	ds_write_b16 v74, v4 offset:10224
	v_pk_mul_f32 v[4:5], v[6:7], v[8:9] op_sel_hi:[0,1]
	v_cvt_f32_f16_e32 v8, v85
	v_cvt_f32_f16_e32 v9, v92
	s_cselect_b64 s[10:11], -1, 0
	s_cmpk_lt_i32 s50, 0x1000
	v_pk_mul_f32 v[10:11], v[6:7], v[10:11] op_sel_hi:[0,1]
	v_pk_mul_f32 v[8:9], v[178:179], v[8:9]
	v_pk_mul_f32 v[34:35], v[6:7], v[34:35] op_sel_hi:[0,1]
	ds_write_b16 v74, v16 offset:10080
	v_cvt_pk_bf16_f32 v16, v8, s0
	s_cselect_b32 s12, s50, -1
	v_pk_mul_f32 v[14:15], v[6:7], v[14:15] op_sel_hi:[0,1]
	v_pk_mul_f32 v[36:37], v[6:7], v[36:37] op_sel_hi:[0,1]
	ds_write_b16 v74, v16 offset:19296
	v_cvt_pk_bf16_f32 v16, v9, s0
	v_pk_mul_f32 v[166:167], v[6:7], v[8:9] op_sel_hi:[0,1]
	v_cvt_pk_bf16_f32 v8, v10, v11
	v_cvt_pk_bf16_f32 v9, v34, v35
	v_cvt_pk_bf16_f32 v10, v176, v177
	v_cvt_pk_bf16_f32 v11, v4, v5
	v_cvt_pk_bf16_f32 v4, v7, v17
	v_cvt_pk_bf16_f32 v5, v20, v38
	v_cvt_pk_bf16_f32 v6, v39, v163
	v_cvt_pk_bf16_f32 v7, v164, v165
	ds_write_b16 v74, v16 offset:19440
	ds_write_b128 v77, v[8:11] offset:36864
	v_cvt_pk_bf16_f32 v8, v14, v15
	v_cvt_pk_bf16_f32 v9, v36, v37
	v_cvt_pk_bf16_f32 v10, v174, v175
	v_cvt_pk_bf16_f32 v11, v166, v167
	ds_write_b128 v77, v[4:7] offset:55296
	v_cvt_pk_bf16_f32 v4, v168, v170
	v_cvt_pk_bf16_f32 v5, v18, v19
	v_cvt_pk_bf16_f32 v6, v172, v173
	v_cvt_pk_bf16_f32 v7, v12, v13
	s_cmp_lt_i32 s12, 0
	ds_write_b128 v77, v[8:11] offset:46080
	ds_write_b128 v79, v[4:7]
	s_cbranch_scc1 .LBB0_925
; __device__ __forceinline__ h16* chunk_base(const Params& p, int item) { return (h16*)(p.ws + WS_SC) + ((size_t)(item >> 7) * SEQ + (size_t)(item & 127) * 64) * 384; }
; __device__ __forceinline__ void chunk_load(const Params& p, int item, int tid, h16 (&raw)[48]) {
;     const h16* base = chunk_base(p, item) + (size_t)(8 * (tid >> 6)) * 384 + (tid & 63);
; #pragma unroll
;     for (int i = 0; i < 8; ++i)
; #pragma unroll
;         for (int vq = 0; vq < 6; ++vq) raw[i * 6 + vq] = base[(size_t)i * 384 + vq * 64];
; }
	s_lshr_b32 s8, s12, 7
	s_lshl_b64 s[14:15], s[8:9], 13
	s_lshl_b32 s8, s12, 6
	s_and_b32 s8, s8, 0x1fc0
	s_or_b32 s8, s14, s8
	v_mad_u64_u32 v[4:5], s[12:13], s8, v160, v[22:23]
	s_mul_i32 s8, s15, 0x300
	v_add_u32_e32 v5, s8, v5
	global_load_ushort v40, v[4:5], off
	global_load_ushort v41, v[4:5], off offset:128
	global_load_ushort v42, v[4:5], off offset:256
	global_load_ushort v43, v[4:5], off offset:384
	global_load_ushort v44, v[4:5], off offset:512
	global_load_ushort v45, v[4:5], off offset:640
	global_load_ushort v46, v[4:5], off offset:768
	global_load_ushort v47, v[4:5], off offset:896
	global_load_ushort v48, v[4:5], off offset:1024
	global_load_ushort v49, v[4:5], off offset:1152
	global_load_ushort v50, v[4:5], off offset:1280
	global_load_ushort v51, v[4:5], off offset:1408
	global_load_ushort v52, v[4:5], off offset:1536
	global_load_ushort v53, v[4:5], off offset:1664
	global_load_ushort v54, v[4:5], off offset:1792
	global_load_ushort v55, v[4:5], off offset:1920
	global_load_ushort v56, v[4:5], off offset:2048
	global_load_ushort v57, v[4:5], off offset:2176
	global_load_ushort v58, v[4:5], off offset:2304
	global_load_ushort v59, v[4:5], off offset:2432
	global_load_ushort v60, v[4:5], off offset:2560
	global_load_ushort v61, v[4:5], off offset:2688
	global_load_ushort v62, v[4:5], off offset:2816
	global_load_ushort v64, v[4:5], off offset:2944
	global_load_ushort v66, v[4:5], off offset:3072
	global_load_ushort v67, v[4:5], off offset:3200
	global_load_ushort v68, v[4:5], off offset:3328
	global_load_ushort v69, v[4:5], off offset:3456
	global_load_ushort v70, v[4:5], off offset:3584
	global_load_ushort v71, v[4:5], off offset:3712
	global_load_ushort v72, v[4:5], off offset:3840
	global_load_ushort v73, v[4:5], off offset:3968
	v_add_co_u32_e32 v4, vcc, s53, v4
	s_nop 1
	v_addc_co_u32_e32 v5, vcc, 0, v5, vcc
	global_load_ushort v75, v[4:5], off
	global_load_ushort v76, v[4:5], off offset:128
	global_load_ushort v78, v[4:5], off offset:256
	global_load_ushort v80, v[4:5], off offset:384
	global_load_ushort v81, v[4:5], off offset:512
	global_load_ushort v82, v[4:5], off offset:640
	global_load_ushort v83, v[4:5], off offset:768
	global_load_ushort v84, v[4:5], off offset:896
	global_load_ushort v85, v[4:5], off offset:1024
	global_load_ushort v86, v[4:5], off offset:1152
	global_load_ushort v87, v[4:5], off offset:1280
	global_load_ushort v88, v[4:5], off offset:1408
	global_load_ushort v89, v[4:5], off offset:1536
	global_load_ushort v90, v[4:5], off offset:1664
	global_load_ushort v92, v[4:5], off offset:1792
	global_load_ushort v93, v[4:5], off offset:1920
